# nt also on the bf16 stores of layer 1's weight conversions (consumed hundreds of us later)
# baseline (speedup 1.0000x reference)
.LBB0_752:
	s_cmpk_gt_u32 s29, 0x7ff
	s_cbranch_scc0 .LBB0_762
	s_cmpk_gt_u32 s29, 0xd7f
	s_cbranch_scc0 .LBB0_759
	s_cmpk_gt_u32 s29, 0x12ff
	s_cbranch_scc0 .LBB0_756
	v_add_u32_e32 v66, v203, v226
	v_add_u32_e32 v78, 0x420, v66
	s_waitcnt vmcnt(7)
	ds_write2_b32 v66, v62, v63 offset1:1
	ds_write2_b32 v66, v64, v65 offset0:2 offset1:3
	s_waitcnt vmcnt(6)
	ds_write2_b32 v78, v58, v59 offset1:1
	v_add_u32_e32 v78, 0x428, v66
	ds_write2_b32 v78, v60, v61 offset1:1
	v_add_u32_e32 v78, 0x840, v66
	s_waitcnt vmcnt(5)
	ds_write2_b32 v78, v54, v55 offset1:1
	v_add_u32_e32 v78, 0x848, v66
	ds_write2_b32 v78, v56, v57 offset1:1
	v_add_u32_e32 v78, 0xc60, v66
	s_waitcnt vmcnt(4)
	ds_write2_b32 v78, v46, v47 offset1:1
	v_add_u32_e32 v78, 0xc68, v66
	ds_write2_b32 v78, v48, v49 offset1:1
	v_add_u32_e32 v78, 0x1080, v66
	s_waitcnt vmcnt(3)
	ds_write2_b32 v78, v50, v51 offset1:1
	v_add_u32_e32 v78, 0x1088, v66
	ds_write2_b32 v78, v52, v53 offset1:1
	v_add_u32_e32 v78, 0x14a0, v66
	s_waitcnt vmcnt(2)
	ds_write2_b32 v78, v38, v39 offset1:1
	v_add_u32_e32 v78, 0x14a8, v66
	ds_write2_b32 v78, v40, v41 offset1:1
	v_add_u32_e32 v78, 0x18c0, v66
	s_waitcnt vmcnt(1)
	ds_write2_b32 v78, v42, v43 offset1:1
	v_add_u32_e32 v78, 0x18c8, v66
	ds_write2_b32 v78, v44, v45 offset1:1
	v_add_u32_e32 v78, 0x1ce0, v66
	v_add_u32_e32 v66, 0x1ce8, v66
	s_waitcnt vmcnt(0)
	ds_write2_b32 v78, v34, v35 offset1:1
	ds_write2_b32 v66, v36, v37 offset1:1
	s_waitcnt lgkmcnt(0)
	ds_read2_b32 v[82:83], v76 offset1:8
	ds_read2_b32 v[86:87], v76 offset0:33 offset1:41
	ds_read2_b32 v[88:89], v76 offset0:66 offset1:74
	ds_read2_b32 v[90:91], v76 offset0:99 offset1:107
	ds_read2_b32 v[92:93], v76 offset0:132 offset1:140
	s_waitcnt lgkmcnt(4)
	v_bfe_u32 v66, v82, 16, 1
	v_add3_u32 v66, v82, v66, s26
	s_waitcnt lgkmcnt(3)
	v_bfe_u32 v78, v86, 16, 1
	v_lshrrev_b32_e32 v66, 16, v66
	v_add3_u32 v78, v86, v78, s26
	ds_read2_b32 v[94:95], v76 offset0:165 offset1:173
	v_and_or_b32 v78, v78, s27, v66
	s_waitcnt lgkmcnt(3)
	v_bfe_u32 v66, v88, 16, 1
	v_add3_u32 v66, v88, v66, s26
	s_waitcnt lgkmcnt(2)
	v_bfe_u32 v79, v90, 16, 1
	ds_read2_b32 v[96:97], v76 offset0:198 offset1:206
	v_lshrrev_b32_e32 v66, 16, v66
	v_add3_u32 v79, v90, v79, s26
	ds_read2_b32 v[98:99], v76 offset0:231 offset1:239
	v_and_or_b32 v79, v79, s27, v66
	s_waitcnt lgkmcnt(3)
	v_bfe_u32 v66, v92, 16, 1
	v_add3_u32 v66, v92, v66, s26
	s_waitcnt lgkmcnt(2)
	v_bfe_u32 v80, v94, 16, 1
	v_lshrrev_b32_e32 v66, 16, v66
	v_add3_u32 v80, v94, v80, s26
	v_and_or_b32 v80, v80, s27, v66
	s_waitcnt lgkmcnt(1)
	v_bfe_u32 v66, v96, 16, 1
	v_add3_u32 v66, v96, v66, s26
	s_waitcnt lgkmcnt(0)
	v_bfe_u32 v81, v98, 16, 1
	s_and_b32 s8, s31, 0xfc0
	s_and_b32 s18, s30, 0x3e0
	v_lshrrev_b32_e32 v66, 16, v66
	v_add3_u32 v81, v98, v81, s26
	s_lshl_b32 s8, s8, 1
	v_and_or_b32 v81, v81, s27, v66
	v_or_b32_e32 v66, s18, v199
	v_lshl_add_u64 v[84:85], v[68:69], 0, s[8:9]
	v_mul_u32_u24_e32 v66, 0x1600, v66
	v_lshl_add_u64 v[100:101], v[84:85], 0, v[66:67]
	v_bfe_u32 v66, v83, 16, 1
	global_store_dwordx4 v[100:101], v[78:81], off sc1 nt
	v_add3_u32 v66, v83, v66, s26
	v_lshrrev_b32_e32 v66, 16, v66
	v_bfe_u32 v78, v87, 16, 1
	v_add3_u32 v78, v87, v78, s26
	v_and_or_b32 v78, v78, s27, v66
	v_bfe_u32 v66, v89, 16, 1
	v_add3_u32 v66, v89, v66, s26
	v_bfe_u32 v79, v91, 16, 1
	v_lshrrev_b32_e32 v66, 16, v66
	v_add3_u32 v79, v91, v79, s26
	v_and_or_b32 v79, v79, s27, v66
	v_bfe_u32 v66, v93, 16, 1
	v_add3_u32 v66, v93, v66, s26
	v_bfe_u32 v80, v95, 16, 1
	v_lshrrev_b32_e32 v66, 16, v66
	v_add3_u32 v80, v95, v80, s26
	v_and_or_b32 v80, v80, s27, v66
	v_bfe_u32 v66, v97, 16, 1
	v_add3_u32 v66, v97, v66, s26
	v_bfe_u32 v81, v99, 16, 1
	v_lshrrev_b32_e32 v66, 16, v66
	v_add3_u32 v81, v99, v81, s26
	v_and_or_b32 v81, v81, s27, v66
	v_or_b32_e32 v66, s18, v227
	v_mul_u32_u24_e32 v66, 0x1600, v66
	ds_read2_b32 v[82:83], v76 offset0:16 offset1:24
	v_lshl_add_u64 v[86:87], v[84:85], 0, v[66:67]
	global_store_dwordx4 v[86:87], v[78:81], off sc1 nt
	ds_read2_b32 v[86:87], v76 offset0:49 offset1:57
	ds_read2_b32 v[88:89], v76 offset0:82 offset1:90
	ds_read2_b32 v[90:91], v76 offset0:115 offset1:123
	s_waitcnt lgkmcnt(3)
	v_bfe_u32 v66, v82, 16, 1
	v_add3_u32 v66, v82, v66, s26
	s_waitcnt lgkmcnt(2)
	v_bfe_u32 v78, v86, 16, 1
	ds_read2_b32 v[92:93], v76 offset0:148 offset1:156
	v_lshrrev_b32_e32 v66, 16, v66
	v_add3_u32 v78, v86, v78, s26
	ds_read2_b32 v[94:95], v76 offset0:181 offset1:189
	v_and_or_b32 v78, v78, s27, v66
	s_waitcnt lgkmcnt(3)
	v_bfe_u32 v66, v88, 16, 1
	v_add3_u32 v66, v88, v66, s26
	s_waitcnt lgkmcnt(2)
	v_bfe_u32 v79, v90, 16, 1
	ds_read2_b32 v[96:97], v76 offset0:214 offset1:222
	v_lshrrev_b32_e32 v66, 16, v66
	v_add3_u32 v79, v90, v79, s26
	ds_read2_b32 v[98:99], v76 offset0:247 offset1:255
	v_and_or_b32 v79, v79, s27, v66
	s_waitcnt lgkmcnt(3)
	v_bfe_u32 v66, v92, 16, 1
	v_add3_u32 v66, v92, v66, s26
	s_waitcnt lgkmcnt(2)
	v_bfe_u32 v80, v94, 16, 1
	v_lshrrev_b32_e32 v66, 16, v66
	v_add3_u32 v80, v94, v80, s26
	v_and_or_b32 v80, v80, s27, v66
	s_waitcnt lgkmcnt(1)
	v_bfe_u32 v66, v96, 16, 1
	v_add3_u32 v66, v96, v66, s26
	s_waitcnt lgkmcnt(0)
	v_bfe_u32 v81, v98, 16, 1
	v_lshrrev_b32_e32 v66, 16, v66
	v_add3_u32 v81, v98, v81, s26
	v_and_or_b32 v81, v81, s27, v66
	v_or_b32_e32 v66, s18, v228
	v_mul_u32_u24_e32 v66, 0x1600, v66
	v_lshl_add_u64 v[100:101], v[84:85], 0, v[66:67]
	v_bfe_u32 v66, v83, 16, 1
	global_store_dwordx4 v[100:101], v[78:81], off sc1 nt
	v_add3_u32 v66, v83, v66, s26
	v_lshrrev_b32_e32 v66, 16, v66
	v_bfe_u32 v78, v87, 16, 1
	v_add3_u32 v78, v87, v78, s26
	v_and_or_b32 v78, v78, s27, v66
	v_bfe_u32 v66, v89, 16, 1
	v_add3_u32 v66, v89, v66, s26
	v_bfe_u32 v79, v91, 16, 1
	v_lshrrev_b32_e32 v66, 16, v66
	v_add3_u32 v79, v91, v79, s26
	v_and_or_b32 v79, v79, s27, v66
	v_bfe_u32 v66, v93, 16, 1
	v_add3_u32 v66, v93, v66, s26
	v_bfe_u32 v80, v95, 16, 1
	v_lshrrev_b32_e32 v66, 16, v66
	v_add3_u32 v80, v95, v80, s26
	v_and_or_b32 v80, v80, s27, v66
	v_bfe_u32 v66, v97, 16, 1
	v_add3_u32 v66, v97, v66, s26
	v_bfe_u32 v81, v99, 16, 1
	v_lshrrev_b32_e32 v66, 16, v66
	v_add3_u32 v81, v99, v81, s26
	v_and_or_b32 v81, v81, s27, v66
	v_or_b32_e32 v66, s18, v229
	v_mul_u32_u24_e32 v66, 0x1600, v66
	v_lshl_add_u64 v[82:83], v[84:85], 0, v[66:67]
	global_store_dwordx4 v[82:83], v[78:81], off sc1 nt
	s_waitcnt lgkmcnt(0)
	s_mov_b64 s[18:19], 0
.LBB0_756:
	s_andn2_b64 vcc, exec, s[18:19]
	s_cbranch_vccnz .LBB0_758
	v_add_u32_e32 v66, v203, v226
	v_add_u32_e32 v78, 0x420, v66
	s_waitcnt vmcnt(7)
	ds_write2_b32 v66, v62, v63 offset1:1
	ds_write2_b32 v66, v64, v65 offset0:2 offset1:3
	s_waitcnt vmcnt(6)
	ds_write2_b32 v78, v58, v59 offset1:1
	v_add_u32_e32 v78, 0x428, v66
	ds_write2_b32 v78, v60, v61 offset1:1
	v_add_u32_e32 v78, 0x840, v66
	s_waitcnt vmcnt(5)
	ds_write2_b32 v78, v54, v55 offset1:1
	v_add_u32_e32 v78, 0x848, v66
	ds_write2_b32 v78, v56, v57 offset1:1
	v_add_u32_e32 v78, 0xc60, v66
	s_waitcnt vmcnt(4)
	ds_write2_b32 v78, v46, v47 offset1:1
	v_add_u32_e32 v78, 0xc68, v66
	ds_write2_b32 v78, v48, v49 offset1:1
	v_add_u32_e32 v78, 0x1080, v66
	s_waitcnt vmcnt(3)
	ds_write2_b32 v78, v50, v51 offset1:1
	v_add_u32_e32 v78, 0x1088, v66
	ds_write2_b32 v78, v52, v53 offset1:1
	v_add_u32_e32 v78, 0x14a0, v66
	s_waitcnt vmcnt(2)
	ds_write2_b32 v78, v38, v39 offset1:1
	v_add_u32_e32 v78, 0x14a8, v66
	ds_write2_b32 v78, v40, v41 offset1:1
	v_add_u32_e32 v78, 0x18c0, v66
	s_waitcnt vmcnt(1)
	ds_write2_b32 v78, v42, v43 offset1:1
	v_add_u32_e32 v78, 0x18c8, v66
	ds_write2_b32 v78, v44, v45 offset1:1
	v_add_u32_e32 v78, 0x1ce0, v66
	v_add_u32_e32 v66, 0x1ce8, v66
	s_waitcnt vmcnt(0)
	ds_write2_b32 v78, v34, v35 offset1:1
	ds_write2_b32 v66, v36, v37 offset1:1
	s_waitcnt lgkmcnt(0)
	ds_read2_b32 v[82:83], v76 offset1:8
	ds_read2_b32 v[86:87], v76 offset0:33 offset1:41
	ds_read2_b32 v[88:89], v76 offset0:66 offset1:74
	ds_read2_b32 v[90:91], v76 offset0:99 offset1:107
	ds_read2_b32 v[92:93], v76 offset0:132 offset1:140
	s_waitcnt lgkmcnt(4)
	v_bfe_u32 v66, v82, 16, 1
	v_add3_u32 v66, v82, v66, s26
	s_waitcnt lgkmcnt(3)
	v_bfe_u32 v78, v86, 16, 1
	s_add_i32 s8, s29, 0xf280
	v_lshrrev_b32_e32 v66, 16, v66
	v_add3_u32 v78, v86, v78, s26
	ds_read2_b32 v[94:95], v76 offset0:165 offset1:173
	s_and_b32 s18, s8, 0xffff
	v_and_or_b32 v78, v78, s27, v66
	s_waitcnt lgkmcnt(3)
	v_bfe_u32 v66, v88, 16, 1
	s_mul_i32 s18, s18, 0xba2f
	v_add3_u32 v66, v88, v66, s26
	s_waitcnt lgkmcnt(2)
	v_bfe_u32 v79, v90, 16, 1
	ds_read2_b32 v[96:97], v76 offset0:198 offset1:206
	s_lshr_b32 s19, s18, 22
	v_lshrrev_b32_e32 v66, 16, v66
	v_add3_u32 v79, v90, v79, s26
	ds_read2_b32 v[98:99], v76 offset0:231 offset1:239
	s_mulk_i32 s19, 0x58
	v_and_or_b32 v79, v79, s27, v66
	s_waitcnt lgkmcnt(3)
	v_bfe_u32 v66, v92, 16, 1
	s_sub_i32 s8, s8, s19
	v_add3_u32 v66, v92, v66, s26
	s_waitcnt lgkmcnt(2)
	v_bfe_u32 v80, v94, 16, 1
	s_lshl_b32 s19, s8, 5
	s_lshl_b32 s8, s8, 6
	v_lshrrev_b32_e32 v66, 16, v66
	v_add3_u32 v80, v94, v80, s26
	s_and_b32 s8, s8, 0x1f00
	s_and_b32 s19, s19, 0x60
	v_and_or_b32 v80, v80, s27, v66
	s_waitcnt lgkmcnt(1)
	v_bfe_u32 v66, v96, 16, 1
	s_or_b32 s8, s19, s8
	v_add3_u32 v66, v96, v66, s26
	s_waitcnt lgkmcnt(0)
	v_bfe_u32 v81, v98, 16, 1
	s_or_b32 s19, s8, 0x80
	s_lshr_b32 s8, s18, 15
	v_lshrrev_b32_e32 v66, 16, v66
	v_add3_u32 v81, v98, v81, s26
	s_and_b32 s8, s8, 0x1ff80
	v_and_or_b32 v81, v81, s27, v66
	v_or_b32_e32 v66, s19, v199
	v_lshl_add_u64 v[84:85], v[70:71], 0, s[8:9]
	v_lshlrev_b32_e32 v66, 11, v66
	v_lshl_add_u64 v[100:101], v[84:85], 0, v[66:67]
	v_bfe_u32 v66, v83, 16, 1
	global_store_dwordx4 v[100:101], v[78:81], off sc1 nt
	v_add3_u32 v66, v83, v66, s26
	v_lshrrev_b32_e32 v66, 16, v66
	v_bfe_u32 v78, v87, 16, 1
	v_add3_u32 v78, v87, v78, s26
	v_and_or_b32 v78, v78, s27, v66
	v_bfe_u32 v66, v89, 16, 1
	v_add3_u32 v66, v89, v66, s26
	v_bfe_u32 v79, v91, 16, 1
	v_lshrrev_b32_e32 v66, 16, v66
	v_add3_u32 v79, v91, v79, s26
	v_and_or_b32 v79, v79, s27, v66
	v_bfe_u32 v66, v93, 16, 1
	v_add3_u32 v66, v93, v66, s26
	v_bfe_u32 v80, v95, 16, 1
	v_lshrrev_b32_e32 v66, 16, v66
	v_add3_u32 v80, v95, v80, s26
	v_and_or_b32 v80, v80, s27, v66
	v_bfe_u32 v66, v97, 16, 1
	v_add3_u32 v66, v97, v66, s26
	v_bfe_u32 v81, v99, 16, 1
	v_lshrrev_b32_e32 v66, 16, v66
	v_add3_u32 v81, v99, v81, s26
	v_and_or_b32 v81, v81, s27, v66
	v_or_b32_e32 v66, s19, v227
	v_lshlrev_b32_e32 v66, 11, v66
	ds_read2_b32 v[82:83], v76 offset0:16 offset1:24
	v_lshl_add_u64 v[86:87], v[84:85], 0, v[66:67]
	global_store_dwordx4 v[86:87], v[78:81], off sc1 nt
	ds_read2_b32 v[86:87], v76 offset0:49 offset1:57
	ds_read2_b32 v[88:89], v76 offset0:82 offset1:90
	ds_read2_b32 v[90:91], v76 offset0:115 offset1:123
	s_waitcnt lgkmcnt(3)
	v_bfe_u32 v66, v82, 16, 1
	v_add3_u32 v66, v82, v66, s26
	s_waitcnt lgkmcnt(2)
	v_bfe_u32 v78, v86, 16, 1
	ds_read2_b32 v[92:93], v76 offset0:148 offset1:156
	v_lshrrev_b32_e32 v66, 16, v66
	v_add3_u32 v78, v86, v78, s26
	ds_read2_b32 v[94:95], v76 offset0:181 offset1:189
	v_and_or_b32 v78, v78, s27, v66
	s_waitcnt lgkmcnt(3)
	v_bfe_u32 v66, v88, 16, 1
	v_add3_u32 v66, v88, v66, s26
	s_waitcnt lgkmcnt(2)
	v_bfe_u32 v79, v90, 16, 1
	ds_read2_b32 v[96:97], v76 offset0:214 offset1:222
	v_lshrrev_b32_e32 v66, 16, v66
	v_add3_u32 v79, v90, v79, s26
	ds_read2_b32 v[98:99], v76 offset0:247 offset1:255
	v_and_or_b32 v79, v79, s27, v66
	s_waitcnt lgkmcnt(3)
	v_bfe_u32 v66, v92, 16, 1
	v_add3_u32 v66, v92, v66, s26
	s_waitcnt lgkmcnt(2)
	v_bfe_u32 v80, v94, 16, 1
	v_lshrrev_b32_e32 v66, 16, v66
	v_add3_u32 v80, v94, v80, s26
	v_and_or_b32 v80, v80, s27, v66
	s_waitcnt lgkmcnt(1)
	v_bfe_u32 v66, v96, 16, 1
	v_add3_u32 v66, v96, v66, s26
	s_waitcnt lgkmcnt(0)
	v_bfe_u32 v81, v98, 16, 1
	v_lshrrev_b32_e32 v66, 16, v66
	v_add3_u32 v81, v98, v81, s26
	v_and_or_b32 v81, v81, s27, v66
	v_or_b32_e32 v66, s19, v228
	v_lshlrev_b32_e32 v66, 11, v66
	v_lshl_add_u64 v[100:101], v[84:85], 0, v[66:67]
	v_bfe_u32 v66, v83, 16, 1
	global_store_dwordx4 v[100:101], v[78:81], off sc1 nt
	v_add3_u32 v66, v83, v66, s26
	v_lshrrev_b32_e32 v66, 16, v66
	v_bfe_u32 v78, v87, 16, 1
	v_add3_u32 v78, v87, v78, s26
	v_and_or_b32 v78, v78, s27, v66
	v_bfe_u32 v66, v89, 16, 1
	v_add3_u32 v66, v89, v66, s26
	v_bfe_u32 v79, v91, 16, 1
	v_lshrrev_b32_e32 v66, 16, v66
	v_add3_u32 v79, v91, v79, s26
	v_and_or_b32 v79, v79, s27, v66
	v_bfe_u32 v66, v93, 16, 1
	v_add3_u32 v66, v93, v66, s26
	v_bfe_u32 v80, v95, 16, 1
	v_lshrrev_b32_e32 v66, 16, v66
	v_add3_u32 v80, v95, v80, s26
	v_and_or_b32 v80, v80, s27, v66
	v_bfe_u32 v66, v97, 16, 1
	v_add3_u32 v66, v97, v66, s26
	v_bfe_u32 v81, v99, 16, 1
	v_lshrrev_b32_e32 v66, 16, v66
	v_add3_u32 v81, v99, v81, s26
	v_and_or_b32 v81, v81, s27, v66
	v_or_b32_e32 v66, s19, v229
	v_lshlrev_b32_e32 v66, 11, v66
	v_lshl_add_u64 v[82:83], v[84:85], 0, v[66:67]
	global_store_dwordx4 v[82:83], v[78:81], off sc1 nt
	s_waitcnt lgkmcnt(0)

.LBB0_759:
	s_andn2_b64 vcc, exec, s[18:19]
	s_cbranch_vccnz .LBB0_761
	v_add_u32_e32 v66, v203, v226
	v_add_u32_e32 v78, 0x420, v66
	s_waitcnt vmcnt(7)
	ds_write2_b32 v66, v62, v63 offset1:1
	ds_write2_b32 v66, v64, v65 offset0:2 offset1:3
	s_waitcnt vmcnt(6)
	ds_write2_b32 v78, v58, v59 offset1:1
	v_add_u32_e32 v78, 0x428, v66
	ds_write2_b32 v78, v60, v61 offset1:1
	v_add_u32_e32 v78, 0x840, v66
	s_waitcnt vmcnt(5)
	ds_write2_b32 v78, v54, v55 offset1:1
	v_add_u32_e32 v78, 0x848, v66
	ds_write2_b32 v78, v56, v57 offset1:1
	v_add_u32_e32 v78, 0xc60, v66
	s_waitcnt vmcnt(4)
	ds_write2_b32 v78, v46, v47 offset1:1
	v_add_u32_e32 v78, 0xc68, v66
	ds_write2_b32 v78, v48, v49 offset1:1
	v_add_u32_e32 v78, 0x1080, v66
	s_waitcnt vmcnt(3)
	ds_write2_b32 v78, v50, v51 offset1:1
	v_add_u32_e32 v78, 0x1088, v66
	ds_write2_b32 v78, v52, v53 offset1:1
	v_add_u32_e32 v78, 0x14a0, v66
	s_waitcnt vmcnt(2)
	ds_write2_b32 v78, v38, v39 offset1:1
	v_add_u32_e32 v78, 0x14a8, v66
	ds_write2_b32 v78, v40, v41 offset1:1
	v_add_u32_e32 v78, 0x18c0, v66
	s_waitcnt vmcnt(1)
	ds_write2_b32 v78, v42, v43 offset1:1
	v_add_u32_e32 v78, 0x18c8, v66
	ds_write2_b32 v78, v44, v45 offset1:1
	v_add_u32_e32 v78, 0x1ce0, v66
	v_add_u32_e32 v66, 0x1ce8, v66
	s_waitcnt vmcnt(0)
	ds_write2_b32 v78, v34, v35 offset1:1
	ds_write2_b32 v66, v36, v37 offset1:1
	s_waitcnt lgkmcnt(0)
	ds_read2_b32 v[82:83], v76 offset1:8
	ds_read2_b32 v[86:87], v76 offset0:33 offset1:41
	ds_read2_b32 v[88:89], v76 offset0:66 offset1:74
	ds_read2_b32 v[90:91], v76 offset0:99 offset1:107
	ds_read2_b32 v[92:93], v76 offset0:132 offset1:140
	s_waitcnt lgkmcnt(4)
	v_bfe_u32 v66, v82, 16, 1
	v_add3_u32 v66, v82, v66, s26
	s_waitcnt lgkmcnt(3)
	v_bfe_u32 v78, v86, 16, 1
	v_lshrrev_b32_e32 v66, 16, v66
	v_add3_u32 v78, v86, v78, s26
	ds_read2_b32 v[94:95], v76 offset0:165 offset1:173
	s_add_i32 s8, s29, 0xf800
	v_and_or_b32 v78, v78, s27, v66
	s_waitcnt lgkmcnt(3)
	v_bfe_u32 v66, v88, 16, 1
	s_and_b32 s18, s8, 0xffff
	v_add3_u32 v66, v88, v66, s26
	s_waitcnt lgkmcnt(2)
	v_bfe_u32 v79, v90, 16, 1
	ds_read2_b32 v[96:97], v76 offset0:198 offset1:206
	s_mul_i32 s18, s18, 0xba2f
	v_lshrrev_b32_e32 v66, 16, v66
	v_add3_u32 v79, v90, v79, s26
	ds_read2_b32 v[98:99], v76 offset0:231 offset1:239
	s_lshr_b32 s19, s18, 22
	v_and_or_b32 v79, v79, s27, v66
	s_waitcnt lgkmcnt(3)
	v_bfe_u32 v66, v92, 16, 1
	s_mulk_i32 s19, 0x58
	v_add3_u32 v66, v92, v66, s26
	s_waitcnt lgkmcnt(2)
	v_bfe_u32 v80, v94, 16, 1
	s_sub_i32 s8, s8, s19
	v_lshrrev_b32_e32 v66, 16, v66
	v_add3_u32 v80, v94, v80, s26
	s_lshl_b32 s19, s8, 5
	s_lshl_b32 s8, s8, 6
	v_and_or_b32 v80, v80, s27, v66
	s_waitcnt lgkmcnt(1)
	v_bfe_u32 v66, v96, 16, 1
	s_and_b32 s8, s8, 0x1f00
	s_and_b32 s19, s19, 0x60
	v_add3_u32 v66, v96, v66, s26
	s_waitcnt lgkmcnt(0)
	v_bfe_u32 v81, v98, 16, 1
	s_or_b32 s19, s8, s19
	s_lshr_b32 s8, s18, 15
	v_lshrrev_b32_e32 v66, 16, v66
	v_add3_u32 v81, v98, v81, s26
	s_and_b32 s8, s8, 0x1ff80
	v_and_or_b32 v81, v81, s27, v66
	v_or_b32_e32 v66, s19, v199
	v_lshl_add_u64 v[84:85], v[70:71], 0, s[8:9]
	v_lshlrev_b32_e32 v66, 11, v66
	v_lshl_add_u64 v[100:101], v[84:85], 0, v[66:67]
	v_bfe_u32 v66, v83, 16, 1
	global_store_dwordx4 v[100:101], v[78:81], off sc1 nt
	v_add3_u32 v66, v83, v66, s26
	v_lshrrev_b32_e32 v66, 16, v66
	v_bfe_u32 v78, v87, 16, 1
	v_add3_u32 v78, v87, v78, s26
	v_and_or_b32 v78, v78, s27, v66
	v_bfe_u32 v66, v89, 16, 1
	v_add3_u32 v66, v89, v66, s26
	v_bfe_u32 v79, v91, 16, 1
	v_lshrrev_b32_e32 v66, 16, v66
	v_add3_u32 v79, v91, v79, s26
	v_and_or_b32 v79, v79, s27, v66
	v_bfe_u32 v66, v93, 16, 1
	v_add3_u32 v66, v93, v66, s26
	v_bfe_u32 v80, v95, 16, 1
	v_lshrrev_b32_e32 v66, 16, v66
	v_add3_u32 v80, v95, v80, s26
	v_and_or_b32 v80, v80, s27, v66
	v_bfe_u32 v66, v97, 16, 1
	v_add3_u32 v66, v97, v66, s26
	v_bfe_u32 v81, v99, 16, 1
	v_lshrrev_b32_e32 v66, 16, v66
	v_add3_u32 v81, v99, v81, s26
	v_and_or_b32 v81, v81, s27, v66
	v_or_b32_e32 v66, s19, v227
	v_lshlrev_b32_e32 v66, 11, v66
	ds_read2_b32 v[82:83], v76 offset0:16 offset1:24
	v_lshl_add_u64 v[86:87], v[84:85], 0, v[66:67]
	global_store_dwordx4 v[86:87], v[78:81], off sc1 nt
	ds_read2_b32 v[86:87], v76 offset0:49 offset1:57
	ds_read2_b32 v[88:89], v76 offset0:82 offset1:90
	ds_read2_b32 v[90:91], v76 offset0:115 offset1:123
	s_waitcnt lgkmcnt(3)
	v_bfe_u32 v66, v82, 16, 1
	v_add3_u32 v66, v82, v66, s26
	s_waitcnt lgkmcnt(2)
	v_bfe_u32 v78, v86, 16, 1
	ds_read2_b32 v[92:93], v76 offset0:148 offset1:156
	v_lshrrev_b32_e32 v66, 16, v66
	v_add3_u32 v78, v86, v78, s26
	ds_read2_b32 v[94:95], v76 offset0:181 offset1:189
	v_and_or_b32 v78, v78, s27, v66
	s_waitcnt lgkmcnt(3)
	v_bfe_u32 v66, v88, 16, 1
	v_add3_u32 v66, v88, v66, s26
	s_waitcnt lgkmcnt(2)
	v_bfe_u32 v79, v90, 16, 1
	ds_read2_b32 v[96:97], v76 offset0:214 offset1:222
	v_lshrrev_b32_e32 v66, 16, v66
	v_add3_u32 v79, v90, v79, s26
	ds_read2_b32 v[98:99], v76 offset0:247 offset1:255
	v_and_or_b32 v79, v79, s27, v66
	s_waitcnt lgkmcnt(3)
	v_bfe_u32 v66, v92, 16, 1
	v_add3_u32 v66, v92, v66, s26
	s_waitcnt lgkmcnt(2)
	v_bfe_u32 v80, v94, 16, 1
	v_lshrrev_b32_e32 v66, 16, v66
	v_add3_u32 v80, v94, v80, s26
	v_and_or_b32 v80, v80, s27, v66
	s_waitcnt lgkmcnt(1)
	v_bfe_u32 v66, v96, 16, 1
	v_add3_u32 v66, v96, v66, s26
	s_waitcnt lgkmcnt(0)
	v_bfe_u32 v81, v98, 16, 1
	v_lshrrev_b32_e32 v66, 16, v66
	v_add3_u32 v81, v98, v81, s26
	v_and_or_b32 v81, v81, s27, v66
	v_or_b32_e32 v66, s19, v228
	v_lshlrev_b32_e32 v66, 11, v66
	v_lshl_add_u64 v[100:101], v[84:85], 0, v[66:67]
	v_bfe_u32 v66, v83, 16, 1
	global_store_dwordx4 v[100:101], v[78:81], off sc1 nt
	v_add3_u32 v66, v83, v66, s26
	v_lshrrev_b32_e32 v66, 16, v66
	v_bfe_u32 v78, v87, 16, 1
	v_add3_u32 v78, v87, v78, s26
	v_and_or_b32 v78, v78, s27, v66
	v_bfe_u32 v66, v89, 16, 1
	v_add3_u32 v66, v89, v66, s26
	v_bfe_u32 v79, v91, 16, 1
	v_lshrrev_b32_e32 v66, 16, v66
	v_add3_u32 v79, v91, v79, s26
	v_and_or_b32 v79, v79, s27, v66
	v_bfe_u32 v66, v93, 16, 1
	v_add3_u32 v66, v93, v66, s26
	v_bfe_u32 v80, v95, 16, 1
	v_lshrrev_b32_e32 v66, 16, v66
	v_add3_u32 v80, v95, v80, s26
	v_and_or_b32 v80, v80, s27, v66
	v_bfe_u32 v66, v97, 16, 1
	v_add3_u32 v66, v97, v66, s26
	v_bfe_u32 v81, v99, 16, 1
	v_lshrrev_b32_e32 v66, 16, v66
	v_add3_u32 v81, v99, v81, s26
	v_and_or_b32 v81, v81, s27, v66
	v_or_b32_e32 v66, s19, v229
	v_lshlrev_b32_e32 v66, 11, v66
	v_lshl_add_u64 v[82:83], v[84:85], 0, v[66:67]
	global_store_dwordx4 v[82:83], v[78:81], off sc1 nt
	s_waitcnt lgkmcnt(0)

.LBB0_762:
	s_andn2_b64 vcc, exec, s[18:19]
	s_cbranch_vccnz .LBB0_764
	v_add_u32_e32 v66, v203, v226
	v_add_u32_e32 v78, 0x420, v66
	s_waitcnt vmcnt(7)
	ds_write2_b32 v66, v62, v63 offset1:1
	ds_write2_b32 v66, v64, v65 offset0:2 offset1:3
	s_waitcnt vmcnt(6)
	ds_write2_b32 v78, v58, v59 offset1:1
	v_add_u32_e32 v78, 0x428, v66
	ds_write2_b32 v78, v60, v61 offset1:1
	v_add_u32_e32 v78, 0x840, v66
	s_waitcnt vmcnt(5)
	ds_write2_b32 v78, v54, v55 offset1:1
	v_add_u32_e32 v78, 0x848, v66
	ds_write2_b32 v78, v56, v57 offset1:1
	v_add_u32_e32 v78, 0xc60, v66
	s_waitcnt vmcnt(4)
	ds_write2_b32 v78, v46, v47 offset1:1
	v_add_u32_e32 v78, 0xc68, v66
	ds_write2_b32 v78, v48, v49 offset1:1
	v_add_u32_e32 v78, 0x1080, v66
	s_waitcnt vmcnt(3)
	ds_write2_b32 v78, v50, v51 offset1:1
	v_add_u32_e32 v78, 0x1088, v66
	ds_write2_b32 v78, v52, v53 offset1:1
	v_add_u32_e32 v78, 0x14a0, v66
	s_waitcnt vmcnt(2)
	ds_write2_b32 v78, v38, v39 offset1:1
	v_add_u32_e32 v78, 0x14a8, v66
	ds_write2_b32 v78, v40, v41 offset1:1
	v_add_u32_e32 v78, 0x18c0, v66
	s_waitcnt vmcnt(1)
	ds_write2_b32 v78, v42, v43 offset1:1
	v_add_u32_e32 v78, 0x18c8, v66
	ds_write2_b32 v78, v44, v45 offset1:1
	v_add_u32_e32 v78, 0x1ce0, v66
	v_add_u32_e32 v66, 0x1ce8, v66
	s_waitcnt vmcnt(0)
	ds_write2_b32 v78, v34, v35 offset1:1
	ds_write2_b32 v66, v36, v37 offset1:1
	s_waitcnt lgkmcnt(0)
	ds_read2_b32 v[82:83], v76 offset1:8
	ds_read2_b32 v[86:87], v76 offset0:33 offset1:41
	ds_read2_b32 v[88:89], v76 offset0:66 offset1:74
	ds_read2_b32 v[90:91], v76 offset0:99 offset1:107
	ds_read2_b32 v[92:93], v76 offset0:132 offset1:140
	s_waitcnt lgkmcnt(4)
	v_bfe_u32 v66, v82, 16, 1
	v_add3_u32 v66, v82, v66, s26
	s_waitcnt lgkmcnt(3)
	v_bfe_u32 v78, v86, 16, 1
	v_lshrrev_b32_e32 v66, 16, v66
	v_add3_u32 v78, v86, v78, s26
	ds_read2_b32 v[94:95], v76 offset0:165 offset1:173
	v_and_or_b32 v78, v78, s27, v66
	s_waitcnt lgkmcnt(3)
	v_bfe_u32 v66, v88, 16, 1
	v_add3_u32 v66, v88, v66, s26
	s_waitcnt lgkmcnt(2)
	v_bfe_u32 v79, v90, 16, 1
	ds_read2_b32 v[96:97], v76 offset0:198 offset1:206
	v_lshrrev_b32_e32 v66, 16, v66
	v_add3_u32 v79, v90, v79, s26
	ds_read2_b32 v[98:99], v76 offset0:231 offset1:239
	v_and_or_b32 v79, v79, s27, v66
	s_waitcnt lgkmcnt(3)
	v_bfe_u32 v66, v92, 16, 1
	v_add3_u32 v66, v92, v66, s26
	s_waitcnt lgkmcnt(2)
	v_bfe_u32 v80, v94, 16, 1
	v_lshrrev_b32_e32 v66, 16, v66
	v_add3_u32 v80, v94, v80, s26
	v_and_or_b32 v80, v80, s27, v66
	s_waitcnt lgkmcnt(1)
	v_bfe_u32 v66, v96, 16, 1
	s_add_i32 s8, s31, 0x1a00
	s_add_i32 s18, s30, 0x1a000
	v_add3_u32 v66, v96, v66, s26
	s_waitcnt lgkmcnt(0)
	v_bfe_u32 v81, v98, 16, 1
	s_and_b32 s8, s8, 0xfc0
	s_and_b32 s18, s18, 0x3e0
	v_lshrrev_b32_e32 v66, 16, v66
	v_add3_u32 v81, v98, v81, s26
	s_lshl_b32 s8, s8, 1
	v_and_or_b32 v81, v81, s27, v66
	v_or_b32_e32 v66, s18, v199
	v_lshl_add_u64 v[84:85], v[72:73], 0, s[8:9]
	v_lshlrev_b32_e32 v66, 11, v66
	v_lshl_add_u64 v[100:101], v[84:85], 0, v[66:67]
	v_bfe_u32 v66, v83, 16, 1
	global_store_dwordx4 v[100:101], v[78:81], off sc1 nt
	v_add3_u32 v66, v83, v66, s26
	v_lshrrev_b32_e32 v66, 16, v66
	v_bfe_u32 v78, v87, 16, 1
	v_add3_u32 v78, v87, v78, s26
	v_and_or_b32 v78, v78, s27, v66
	v_bfe_u32 v66, v89, 16, 1
	v_add3_u32 v66, v89, v66, s26
	v_bfe_u32 v79, v91, 16, 1
	v_lshrrev_b32_e32 v66, 16, v66
	v_add3_u32 v79, v91, v79, s26
	v_and_or_b32 v79, v79, s27, v66
	v_bfe_u32 v66, v93, 16, 1
	v_add3_u32 v66, v93, v66, s26
	v_bfe_u32 v80, v95, 16, 1
	v_lshrrev_b32_e32 v66, 16, v66
	v_add3_u32 v80, v95, v80, s26
	v_and_or_b32 v80, v80, s27, v66
	v_bfe_u32 v66, v97, 16, 1
	v_add3_u32 v66, v97, v66, s26
	v_bfe_u32 v81, v99, 16, 1
	v_lshrrev_b32_e32 v66, 16, v66
	v_add3_u32 v81, v99, v81, s26
	v_and_or_b32 v81, v81, s27, v66
	v_or_b32_e32 v66, s18, v227
	v_lshlrev_b32_e32 v66, 11, v66
	ds_read2_b32 v[82:83], v76 offset0:16 offset1:24
	v_lshl_add_u64 v[86:87], v[84:85], 0, v[66:67]
	global_store_dwordx4 v[86:87], v[78:81], off sc1 nt
	ds_read2_b32 v[86:87], v76 offset0:49 offset1:57
	ds_read2_b32 v[88:89], v76 offset0:82 offset1:90
	ds_read2_b32 v[90:91], v76 offset0:115 offset1:123
	s_waitcnt lgkmcnt(3)
	v_bfe_u32 v66, v82, 16, 1
	v_add3_u32 v66, v82, v66, s26
	s_waitcnt lgkmcnt(2)
	v_bfe_u32 v78, v86, 16, 1
	ds_read2_b32 v[92:93], v76 offset0:148 offset1:156
	v_lshrrev_b32_e32 v66, 16, v66
	v_add3_u32 v78, v86, v78, s26
	ds_read2_b32 v[94:95], v76 offset0:181 offset1:189
	v_and_or_b32 v78, v78, s27, v66
	s_waitcnt lgkmcnt(3)
	v_bfe_u32 v66, v88, 16, 1
	v_add3_u32 v66, v88, v66, s26
	s_waitcnt lgkmcnt(2)
	v_bfe_u32 v79, v90, 16, 1
	ds_read2_b32 v[96:97], v76 offset0:214 offset1:222
	v_lshrrev_b32_e32 v66, 16, v66
	v_add3_u32 v79, v90, v79, s26
	ds_read2_b32 v[98:99], v76 offset0:247 offset1:255
	v_and_or_b32 v79, v79, s27, v66
	s_waitcnt lgkmcnt(3)
	v_bfe_u32 v66, v92, 16, 1
	v_add3_u32 v66, v92, v66, s26
	s_waitcnt lgkmcnt(2)
	v_bfe_u32 v80, v94, 16, 1
	v_lshrrev_b32_e32 v66, 16, v66
	v_add3_u32 v80, v94, v80, s26
	v_and_or_b32 v80, v80, s27, v66
	s_waitcnt lgkmcnt(1)
	v_bfe_u32 v66, v96, 16, 1
	v_add3_u32 v66, v96, v66, s26
	s_waitcnt lgkmcnt(0)
	v_bfe_u32 v81, v98, 16, 1
	v_lshrrev_b32_e32 v66, 16, v66
	v_add3_u32 v81, v98, v81, s26
	v_and_or_b32 v81, v81, s27, v66
	v_or_b32_e32 v66, s18, v228
	v_lshlrev_b32_e32 v66, 11, v66
	v_lshl_add_u64 v[100:101], v[84:85], 0, v[66:67]
	v_bfe_u32 v66, v83, 16, 1
	global_store_dwordx4 v[100:101], v[78:81], off sc1 nt
	v_add3_u32 v66, v83, v66, s26
	v_lshrrev_b32_e32 v66, 16, v66
	v_bfe_u32 v78, v87, 16, 1
	v_add3_u32 v78, v87, v78, s26
	v_and_or_b32 v78, v78, s27, v66
	v_bfe_u32 v66, v89, 16, 1
	v_add3_u32 v66, v89, v66, s26
	v_bfe_u32 v79, v91, 16, 1
	v_lshrrev_b32_e32 v66, 16, v66
	v_add3_u32 v79, v91, v79, s26
	v_and_or_b32 v79, v79, s27, v66
	v_bfe_u32 v66, v93, 16, 1
	v_add3_u32 v66, v93, v66, s26
	v_bfe_u32 v80, v95, 16, 1
	v_lshrrev_b32_e32 v66, 16, v66
	v_add3_u32 v80, v95, v80, s26
	v_and_or_b32 v80, v80, s27, v66
	v_bfe_u32 v66, v97, 16, 1
	v_add3_u32 v66, v97, v66, s26
	v_bfe_u32 v81, v99, 16, 1
	v_lshrrev_b32_e32 v66, 16, v66
	v_add3_u32 v81, v99, v81, s26
	v_and_or_b32 v81, v81, s27, v66
	v_or_b32_e32 v66, s18, v229
	v_lshlrev_b32_e32 v66, 11, v66
	v_lshl_add_u64 v[82:83], v[84:85], 0, v[66:67]
	global_store_dwordx4 v[82:83], v[78:81], off sc1 nt
	s_waitcnt lgkmcnt(0)

.LBB0_771:
	s_mul_hi_i32 s8, s29, 0x2aaaaaab
	s_lshr_b32 s18, s8, 31
	s_ashr_i32 s8, s8, 4
	s_add_i32 s8, s8, s18
	s_mul_i32 s18, s8, 0xffffffa0
	s_add_i32 s19, s29, s18
	s_lshl_b32 s18, s8, 6
	s_cmp_lt_i32 s19, 16
	s_cselect_b64 vcc, -1, 0
	v_cndmask_b32_e32 v66, 1.0, v77, vcc
	s_waitcnt vmcnt(7)
	v_pk_mul_f32 v[62:63], v[66:67], v[62:63] op_sel_hi:[0,1]
	v_add_u32_e32 v78, v203, v226
	ds_write2_b32 v78, v62, v63 offset1:1
	v_pk_mul_f32 v[62:63], v[66:67], v[64:65] op_sel_hi:[0,1]
	ds_write2_b32 v78, v62, v63 offset0:2 offset1:3
	s_waitcnt vmcnt(6)
	v_pk_mul_f32 v[58:59], v[66:67], v[58:59] op_sel_hi:[0,1]
	v_add_u32_e32 v62, 0x420, v78
	ds_write2_b32 v62, v58, v59 offset1:1
	v_pk_mul_f32 v[58:59], v[66:67], v[60:61] op_sel_hi:[0,1]
	v_add_u32_e32 v60, 0x428, v78
	ds_write2_b32 v60, v58, v59 offset1:1
	s_waitcnt vmcnt(5)
	v_pk_mul_f32 v[54:55], v[66:67], v[54:55] op_sel_hi:[0,1]
	v_add_u32_e32 v58, 0x840, v78
	ds_write2_b32 v58, v54, v55 offset1:1
	v_pk_mul_f32 v[54:55], v[66:67], v[56:57] op_sel_hi:[0,1]
	v_add_u32_e32 v56, 0x848, v78
	ds_write2_b32 v56, v54, v55 offset1:1
	s_waitcnt vmcnt(4)
	v_pk_mul_f32 v[46:47], v[66:67], v[46:47] op_sel_hi:[0,1]
	v_add_u32_e32 v54, 0xc60, v78
	ds_write2_b32 v54, v46, v47 offset1:1
	v_pk_mul_f32 v[46:47], v[66:67], v[48:49] op_sel_hi:[0,1]
	v_add_u32_e32 v48, 0xc68, v78
	ds_write2_b32 v48, v46, v47 offset1:1
	s_waitcnt vmcnt(3)
	v_pk_mul_f32 v[46:47], v[66:67], v[50:51] op_sel_hi:[0,1]
	v_add_u32_e32 v48, 0x1080, v78
	ds_write2_b32 v48, v46, v47 offset1:1
	v_pk_mul_f32 v[46:47], v[66:67], v[52:53] op_sel_hi:[0,1]
	v_add_u32_e32 v48, 0x1088, v78
	ds_write2_b32 v48, v46, v47 offset1:1
	s_waitcnt vmcnt(2)
	v_pk_mul_f32 v[38:39], v[66:67], v[38:39] op_sel_hi:[0,1]
	v_add_u32_e32 v46, 0x14a0, v78
	ds_write2_b32 v46, v38, v39 offset1:1
	v_pk_mul_f32 v[38:39], v[66:67], v[40:41] op_sel_hi:[0,1]
	v_add_u32_e32 v40, 0x14a8, v78
	ds_write2_b32 v40, v38, v39 offset1:1
	s_waitcnt vmcnt(1)
	v_pk_mul_f32 v[38:39], v[42:43], v[66:67] op_sel_hi:[1,0]
	v_add_u32_e32 v40, 0x18c0, v78
	ds_write2_b32 v40, v38, v39 offset1:1
	v_pk_mul_f32 v[38:39], v[44:45], v[66:67] op_sel_hi:[1,0]
	v_add_u32_e32 v40, 0x18c8, v78
	ds_write2_b32 v40, v38, v39 offset1:1
	s_waitcnt vmcnt(0)
	v_pk_mul_f32 v[34:35], v[34:35], v[66:67] op_sel_hi:[1,0]
	v_add_u32_e32 v38, 0x1ce0, v78
	ds_write2_b32 v38, v34, v35 offset1:1
	v_pk_mul_f32 v[34:35], v[36:37], v[66:67] op_sel_hi:[1,0]
	v_add_u32_e32 v36, 0x1ce8, v78
	ds_write2_b32 v36, v34, v35 offset1:1
	s_waitcnt lgkmcnt(0)
	ds_read2_b32 v[38:39], v76 offset1:8
	ds_read2_b32 v[42:43], v76 offset0:33 offset1:41
	ds_read2_b32 v[44:45], v76 offset0:66 offset1:74
	ds_read2_b32 v[46:47], v76 offset0:99 offset1:107
	ds_read2_b32 v[48:49], v76 offset0:132 offset1:140
	s_waitcnt lgkmcnt(4)
	v_bfe_u32 v34, v38, 16, 1
	v_add3_u32 v34, v38, v34, s26
	s_waitcnt lgkmcnt(3)
	v_bfe_u32 v35, v42, 16, 1
	v_lshrrev_b32_e32 v34, 16, v34
	v_add3_u32 v35, v42, v35, s26
	ds_read2_b32 v[50:51], v76 offset0:165 offset1:173
	v_and_or_b32 v34, v35, s27, v34
	s_waitcnt lgkmcnt(3)
	v_bfe_u32 v35, v44, 16, 1
	v_add3_u32 v35, v44, v35, s26
	s_waitcnt lgkmcnt(2)
	v_bfe_u32 v36, v46, 16, 1
	ds_read2_b32 v[52:53], v76 offset0:198 offset1:206
	v_lshrrev_b32_e32 v35, 16, v35
	v_add3_u32 v36, v46, v36, s26
	ds_read2_b32 v[54:55], v76 offset0:231 offset1:239
	v_and_or_b32 v35, v36, s27, v35
	s_waitcnt lgkmcnt(3)
	v_bfe_u32 v36, v48, 16, 1
	s_mulk_i32 s8, 0xf400
	v_add3_u32 v36, v48, v36, s26
	s_waitcnt lgkmcnt(2)
	v_bfe_u32 v37, v50, 16, 1
	s_add_i32 s8, s8, s30
	v_lshrrev_b32_e32 v36, 16, v36
	v_add3_u32 v37, v50, v37, s26
	v_add_u32_e32 v58, s8, v199
	v_and_or_b32 v36, v37, s27, v36
	s_waitcnt lgkmcnt(1)
	v_bfe_u32 v37, v52, 16, 1
	v_add_u32_e32 v56, 0x26000, v58
	s_ashr_i32 s19, s18, 31
	v_add3_u32 v37, v52, v37, s26
	s_waitcnt lgkmcnt(0)
	v_bfe_u32 v38, v54, 16, 1
	v_ashrrev_i32_e32 v57, 31, v56
	v_lshl_add_u64 v[40:41], s[18:19], 1, v[74:75]
	v_lshrrev_b32_e32 v37, 16, v37
	v_add3_u32 v38, v54, v38, s26
	v_lshlrev_b64 v[56:57], 11, v[56:57]
	v_and_or_b32 v37, v38, s27, v37
	v_lshl_add_u64 v[56:57], v[40:41], 0, v[56:57]
	global_store_dwordx4 v[56:57], v[34:37], off sc1 nt
	v_bfe_u32 v38, v55, 16, 1
	v_add3_u32 v38, v55, v38, s26
	v_bfe_u32 v34, v39, 16, 1
	v_add3_u32 v34, v39, v34, s26
	v_bfe_u32 v35, v43, 16, 1
	v_lshrrev_b32_e32 v34, 16, v34
	v_add3_u32 v35, v43, v35, s26
	v_and_or_b32 v34, v35, s27, v34
	v_bfe_u32 v35, v45, 16, 1
	v_add3_u32 v35, v45, v35, s26
	v_bfe_u32 v36, v47, 16, 1
	v_lshrrev_b32_e32 v35, 16, v35
	v_add3_u32 v36, v47, v36, s26
	v_and_or_b32 v35, v36, s27, v35
	v_bfe_u32 v36, v49, 16, 1
	v_add3_u32 v36, v49, v36, s26
	v_bfe_u32 v37, v51, 16, 1
	v_lshrrev_b32_e32 v36, 16, v36
	v_add3_u32 v37, v51, v37, s26
	v_and_or_b32 v36, v37, s27, v36
	v_bfe_u32 v37, v53, 16, 1
	v_add3_u32 v37, v53, v37, s26
	v_lshrrev_b32_e32 v37, 16, v37
	v_and_or_b32 v37, v38, s27, v37
	v_add_u32_e32 v38, 0x26008, v58
	v_ashrrev_i32_e32 v39, 31, v38
	v_lshlrev_b64 v[38:39], 11, v[38:39]
	ds_read2_b32 v[42:43], v76 offset0:16 offset1:24
	v_lshl_add_u64 v[38:39], v[40:41], 0, v[38:39]
	global_store_dwordx4 v[38:39], v[34:37], off sc1 nt
	ds_read2_b32 v[38:39], v76 offset0:49 offset1:57
	ds_read2_b32 v[44:45], v76 offset0:82 offset1:90
	ds_read2_b32 v[46:47], v76 offset0:115 offset1:123
	s_waitcnt lgkmcnt(3)
	v_bfe_u32 v34, v42, 16, 1
	v_add3_u32 v34, v42, v34, s26
	s_waitcnt lgkmcnt(2)
	v_bfe_u32 v35, v38, 16, 1
	ds_read2_b32 v[48:49], v76 offset0:148 offset1:156
	v_lshrrev_b32_e32 v34, 16, v34
	v_add3_u32 v35, v38, v35, s26
	ds_read2_b32 v[50:51], v76 offset0:181 offset1:189
	v_and_or_b32 v34, v35, s27, v34
	s_waitcnt lgkmcnt(3)
	v_bfe_u32 v35, v44, 16, 1
	v_add3_u32 v35, v44, v35, s26
	s_waitcnt lgkmcnt(2)
	v_bfe_u32 v36, v46, 16, 1
	ds_read2_b32 v[52:53], v76 offset0:214 offset1:222
	v_lshrrev_b32_e32 v35, 16, v35
	v_add3_u32 v36, v46, v36, s26
	ds_read2_b32 v[54:55], v76 offset0:247 offset1:255
	v_and_or_b32 v35, v36, s27, v35
	s_waitcnt lgkmcnt(3)
	v_bfe_u32 v36, v48, 16, 1
	v_add3_u32 v36, v48, v36, s26
	s_waitcnt lgkmcnt(2)
	v_bfe_u32 v37, v50, 16, 1
	v_lshrrev_b32_e32 v36, 16, v36
	v_add3_u32 v37, v50, v37, s26
	v_and_or_b32 v36, v37, s27, v36
	s_waitcnt lgkmcnt(1)
	v_bfe_u32 v37, v52, 16, 1
	v_add_u32_e32 v56, 0x26010, v58
	v_add3_u32 v37, v52, v37, s26
	s_waitcnt lgkmcnt(0)
	v_bfe_u32 v38, v54, 16, 1
	v_ashrrev_i32_e32 v57, 31, v56
	v_lshrrev_b32_e32 v37, 16, v37
	v_add3_u32 v38, v54, v38, s26
	v_lshlrev_b64 v[56:57], 11, v[56:57]
	v_and_or_b32 v37, v38, s27, v37
	v_lshl_add_u64 v[56:57], v[40:41], 0, v[56:57]
	global_store_dwordx4 v[56:57], v[34:37], off sc1 nt
	v_bfe_u32 v38, v55, 16, 1
	v_add3_u32 v38, v55, v38, s26
	v_bfe_u32 v34, v43, 16, 1
	v_add3_u32 v34, v43, v34, s26
	v_bfe_u32 v35, v39, 16, 1
	v_lshrrev_b32_e32 v34, 16, v34
	v_add3_u32 v35, v39, v35, s26
	v_and_or_b32 v34, v35, s27, v34
	v_bfe_u32 v35, v45, 16, 1
	v_add3_u32 v35, v45, v35, s26
	v_bfe_u32 v36, v47, 16, 1
	v_lshrrev_b32_e32 v35, 16, v35
	v_add3_u32 v36, v47, v36, s26
	v_and_or_b32 v35, v36, s27, v35
	v_bfe_u32 v36, v49, 16, 1
	v_add3_u32 v36, v49, v36, s26
	v_bfe_u32 v37, v51, 16, 1
	v_lshrrev_b32_e32 v36, 16, v36
	v_add3_u32 v37, v51, v37, s26
	v_and_or_b32 v36, v37, s27, v36
	v_bfe_u32 v37, v53, 16, 1
	v_add3_u32 v37, v53, v37, s26
	v_lshrrev_b32_e32 v37, 16, v37
	v_and_or_b32 v37, v38, s27, v37
	v_add_u32_e32 v38, 0x26018, v58
	v_ashrrev_i32_e32 v39, 31, v38
	v_lshlrev_b64 v[38:39], 11, v[38:39]
	v_lshl_add_u64 v[38:39], v[40:41], 0, v[38:39]
	global_store_dwordx4 v[38:39], v[34:37], off sc1 nt
	s_waitcnt lgkmcnt(0)
	s_add_i32 s30, s30, 0x8000
	s_andn2_b64 vcc, exec, s[16:17]
	s_addk_i32 s31, 0x800
	s_cbranch_vccz .LBB0_721

.LBB0_1019:
	s_cmpk_gt_u32 s25, 0x7ff
	s_cbranch_scc0 .LBB0_1025
	v_add_u32_e32 v77, v203, v226
	v_add_u32_e32 v78, 0x420, v77
	s_waitcnt vmcnt(15)
	ds_write2_b32 v77, v54, v55 offset1:1
	ds_write2_b32 v77, v56, v57 offset0:2 offset1:3
	s_waitcnt vmcnt(14)
	ds_write2_b32 v78, v50, v51 offset1:1
	v_add_u32_e32 v78, 0x428, v77
	ds_write2_b32 v78, v52, v53 offset1:1
	v_add_u32_e32 v78, 0x840, v77
	s_waitcnt vmcnt(13)
	ds_write2_b32 v78, v42, v43 offset1:1
	v_add_u32_e32 v78, 0x848, v77
	ds_write2_b32 v78, v44, v45 offset1:1
	v_add_u32_e32 v78, 0xc60, v77
	s_waitcnt vmcnt(12)
	ds_write2_b32 v78, v30, v31 offset1:1
	v_add_u32_e32 v78, 0xc68, v77
	ds_write2_b32 v78, v32, v33 offset1:1
	v_add_u32_e32 v78, 0x1080, v77
	s_waitcnt vmcnt(11)
	ds_write2_b32 v78, v34, v35 offset1:1
	v_add_u32_e32 v78, 0x1088, v77
	ds_write2_b32 v78, v36, v37 offset1:1
	v_add_u32_e32 v78, 0x14a0, v77
	s_waitcnt vmcnt(10)
	ds_write2_b32 v78, v22, v23 offset1:1
	v_add_u32_e32 v78, 0x14a8, v77
	ds_write2_b32 v78, v24, v25 offset1:1
	v_add_u32_e32 v78, 0x18c0, v77
	s_waitcnt vmcnt(9)
	ds_write2_b32 v78, v26, v27 offset1:1
	v_add_u32_e32 v78, 0x18c8, v77
	s_cmpk_gt_u32 s25, 0xd7f
	ds_write2_b32 v78, v28, v29 offset1:1
	v_add_u32_e32 v78, 0x1ce0, v77
	v_add_u32_e32 v77, 0x1ce8, v77
	s_waitcnt vmcnt(8)
	ds_write2_b32 v78, v10, v11 offset1:1
	ds_write2_b32 v77, v12, v13 offset1:1
	s_cbranch_scc0 .LBB0_1022
	s_waitcnt lgkmcnt(0)
	ds_read2_b32 v[82:83], v75 offset1:8
	ds_read2_b32 v[86:87], v75 offset0:33 offset1:41
	ds_read2_b32 v[88:89], v75 offset0:66 offset1:74
	ds_read2_b32 v[90:91], v75 offset0:99 offset1:107
	ds_read2_b32 v[92:93], v75 offset0:132 offset1:140
	s_waitcnt lgkmcnt(4)
	v_bfe_u32 v77, v82, 16, 1
	v_add3_u32 v77, v82, v77, s22
	s_waitcnt lgkmcnt(3)
	v_bfe_u32 v78, v86, 16, 1
	s_add_i32 s6, s25, 0xf280
	v_lshrrev_b32_e32 v77, 16, v77
	v_add3_u32 v78, v86, v78, s22
	ds_read2_b32 v[94:95], v75 offset0:165 offset1:173
	s_and_b32 s10, s6, 0xffff
	v_and_or_b32 v78, v78, s23, v77
	s_waitcnt lgkmcnt(3)
	v_bfe_u32 v77, v88, 16, 1
	s_mul_i32 s10, s10, 0xba2f
	v_add3_u32 v77, v88, v77, s22
	s_waitcnt lgkmcnt(2)
	v_bfe_u32 v79, v90, 16, 1
	ds_read2_b32 v[96:97], v75 offset0:198 offset1:206
	s_lshr_b32 s11, s10, 22
	v_lshrrev_b32_e32 v77, 16, v77
	v_add3_u32 v79, v90, v79, s22
	ds_read2_b32 v[98:99], v75 offset0:231 offset1:239
	s_mulk_i32 s11, 0x58
	v_and_or_b32 v79, v79, s23, v77
	s_waitcnt lgkmcnt(3)
	v_bfe_u32 v77, v92, 16, 1
	s_sub_i32 s6, s6, s11
	v_add3_u32 v77, v92, v77, s22
	s_waitcnt lgkmcnt(2)
	v_bfe_u32 v80, v94, 16, 1
	s_lshl_b32 s11, s6, 5
	s_lshl_b32 s6, s6, 6
	v_lshrrev_b32_e32 v77, 16, v77
	v_add3_u32 v80, v94, v80, s22
	s_and_b32 s6, s6, 0x1f00
	s_and_b32 s11, s11, 0x60
	v_and_or_b32 v80, v80, s23, v77
	s_waitcnt lgkmcnt(1)
	v_bfe_u32 v77, v96, 16, 1
	s_or_b32 s6, s11, s6
	v_add3_u32 v77, v96, v77, s22
	s_waitcnt lgkmcnt(0)
	v_bfe_u32 v81, v98, 16, 1
	s_or_b32 s11, s6, 0x80
	s_lshr_b32 s6, s10, 15
	v_lshrrev_b32_e32 v77, 16, v77
	v_add3_u32 v81, v98, v81, s22
	s_and_b32 s6, s6, 0x1ff80
	v_and_or_b32 v81, v81, s23, v77
	v_or_b32_e32 v77, s11, v199
	v_lshl_add_u64 v[84:85], v[68:69], 0, s[6:7]
	v_lshlrev_b32_e32 v100, 11, v77
	v_mov_b32_e32 v101, v67
	v_lshl_add_u64 v[100:101], v[84:85], 0, v[100:101]
	v_bfe_u32 v77, v83, 16, 1
	global_store_dwordx4 v[100:101], v[78:81], off sc1 nt
	v_add3_u32 v77, v83, v77, s22
	v_lshrrev_b32_e32 v77, 16, v77
	v_bfe_u32 v78, v87, 16, 1
	v_add3_u32 v78, v87, v78, s22
	v_and_or_b32 v78, v78, s23, v77
	v_bfe_u32 v77, v89, 16, 1
	v_add3_u32 v77, v89, v77, s22
	v_bfe_u32 v79, v91, 16, 1
	v_lshrrev_b32_e32 v77, 16, v77
	v_add3_u32 v79, v91, v79, s22
	v_and_or_b32 v79, v79, s23, v77
	v_bfe_u32 v77, v93, 16, 1
	v_add3_u32 v77, v93, v77, s22
	v_bfe_u32 v80, v95, 16, 1
	v_lshrrev_b32_e32 v77, 16, v77
	v_add3_u32 v80, v95, v80, s22
	v_and_or_b32 v80, v80, s23, v77
	v_bfe_u32 v77, v97, 16, 1
	v_add3_u32 v77, v97, v77, s22
	v_bfe_u32 v81, v99, 16, 1
	v_lshrrev_b32_e32 v77, 16, v77
	v_add3_u32 v81, v99, v81, s22
	v_and_or_b32 v81, v81, s23, v77
	v_or_b32_e32 v77, s11, v227
	v_lshlrev_b32_e32 v82, 11, v77
	v_mov_b32_e32 v83, v67
	ds_read2_b32 v[86:87], v75 offset0:16 offset1:24
	v_lshl_add_u64 v[82:83], v[84:85], 0, v[82:83]
	global_store_dwordx4 v[82:83], v[78:81], off sc1 nt
	ds_read2_b32 v[82:83], v75 offset0:49 offset1:57
	ds_read2_b32 v[88:89], v75 offset0:82 offset1:90
	ds_read2_b32 v[90:91], v75 offset0:115 offset1:123
	s_waitcnt lgkmcnt(3)
	v_bfe_u32 v77, v86, 16, 1
	v_add3_u32 v77, v86, v77, s22
	s_waitcnt lgkmcnt(2)
	v_bfe_u32 v78, v82, 16, 1
	ds_read2_b32 v[92:93], v75 offset0:148 offset1:156
	v_lshrrev_b32_e32 v77, 16, v77
	v_add3_u32 v78, v82, v78, s22
	ds_read2_b32 v[94:95], v75 offset0:181 offset1:189
	v_and_or_b32 v78, v78, s23, v77
	s_waitcnt lgkmcnt(3)
	v_bfe_u32 v77, v88, 16, 1
	v_add3_u32 v77, v88, v77, s22
	s_waitcnt lgkmcnt(2)
	v_bfe_u32 v79, v90, 16, 1
	ds_read2_b32 v[96:97], v75 offset0:214 offset1:222
	v_lshrrev_b32_e32 v77, 16, v77
	v_add3_u32 v79, v90, v79, s22
	ds_read2_b32 v[98:99], v75 offset0:247 offset1:255
	v_and_or_b32 v79, v79, s23, v77
	s_waitcnt lgkmcnt(3)
	v_bfe_u32 v77, v92, 16, 1
	v_add3_u32 v77, v92, v77, s22
	s_waitcnt lgkmcnt(2)
	v_bfe_u32 v80, v94, 16, 1
	v_lshrrev_b32_e32 v77, 16, v77
	v_add3_u32 v80, v94, v80, s22
	v_and_or_b32 v80, v80, s23, v77
	s_waitcnt lgkmcnt(1)
	v_bfe_u32 v77, v96, 16, 1
	v_add3_u32 v77, v96, v77, s22
	s_waitcnt lgkmcnt(0)
	v_bfe_u32 v81, v98, 16, 1
	v_lshrrev_b32_e32 v77, 16, v77
	v_add3_u32 v81, v98, v81, s22
	v_and_or_b32 v81, v81, s23, v77
	v_or_b32_e32 v77, s11, v228
	v_lshlrev_b32_e32 v100, 11, v77
	v_mov_b32_e32 v101, v67
	v_lshl_add_u64 v[100:101], v[84:85], 0, v[100:101]
	v_bfe_u32 v77, v87, 16, 1
	global_store_dwordx4 v[100:101], v[78:81], off sc1 nt
	v_add3_u32 v77, v87, v77, s22
	v_lshrrev_b32_e32 v77, 16, v77
	v_bfe_u32 v78, v83, 16, 1
	v_add3_u32 v78, v83, v78, s22
	v_and_or_b32 v78, v78, s23, v77
	v_bfe_u32 v77, v89, 16, 1
	v_add3_u32 v77, v89, v77, s22
	v_bfe_u32 v79, v91, 16, 1
	v_lshrrev_b32_e32 v77, 16, v77
	v_add3_u32 v79, v91, v79, s22
	v_and_or_b32 v79, v79, s23, v77
	v_bfe_u32 v77, v93, 16, 1
	v_add3_u32 v77, v93, v77, s22
	v_bfe_u32 v80, v95, 16, 1
	v_lshrrev_b32_e32 v77, 16, v77
	v_add3_u32 v80, v95, v80, s22
	v_and_or_b32 v80, v80, s23, v77
	v_bfe_u32 v77, v97, 16, 1
	v_add3_u32 v77, v97, v77, s22
	v_bfe_u32 v81, v99, 16, 1
	v_lshrrev_b32_e32 v77, 16, v77
	v_add3_u32 v81, v99, v81, s22
	v_and_or_b32 v81, v81, s23, v77
	v_or_b32_e32 v77, s11, v229
	v_lshlrev_b32_e32 v82, 11, v77
	v_mov_b32_e32 v83, v67
	v_lshl_add_u64 v[82:83], v[84:85], 0, v[82:83]
	global_store_dwordx4 v[82:83], v[78:81], off sc1 nt
	s_waitcnt lgkmcnt(0)
	s_mov_b64 s[10:11], 0
.LBB0_1022:
	s_andn2_b64 vcc, exec, s[10:11]
	s_cbranch_vccnz .LBB0_1024
	s_waitcnt lgkmcnt(0)
	ds_read2_b32 v[82:83], v75 offset1:8
	ds_read2_b32 v[86:87], v75 offset0:33 offset1:41
	ds_read2_b32 v[88:89], v75 offset0:66 offset1:74
	ds_read2_b32 v[90:91], v75 offset0:99 offset1:107
	ds_read2_b32 v[92:93], v75 offset0:132 offset1:140
	s_waitcnt lgkmcnt(4)
	v_bfe_u32 v77, v82, 16, 1
	v_add3_u32 v77, v82, v77, s22
	s_waitcnt lgkmcnt(3)
	v_bfe_u32 v78, v86, 16, 1
	v_lshrrev_b32_e32 v77, 16, v77
	v_add3_u32 v78, v86, v78, s22
	ds_read2_b32 v[94:95], v75 offset0:165 offset1:173
	s_add_i32 s6, s25, 0xf800
	v_and_or_b32 v78, v78, s23, v77
	s_waitcnt lgkmcnt(3)
	v_bfe_u32 v77, v88, 16, 1
	s_and_b32 s10, s6, 0xffff
	v_add3_u32 v77, v88, v77, s22
	s_waitcnt lgkmcnt(2)
	v_bfe_u32 v79, v90, 16, 1
	ds_read2_b32 v[96:97], v75 offset0:198 offset1:206
	s_mul_i32 s10, s10, 0xba2f
	v_lshrrev_b32_e32 v77, 16, v77
	v_add3_u32 v79, v90, v79, s22
	ds_read2_b32 v[98:99], v75 offset0:231 offset1:239
	s_lshr_b32 s11, s10, 22
	v_and_or_b32 v79, v79, s23, v77
	s_waitcnt lgkmcnt(3)
	v_bfe_u32 v77, v92, 16, 1
	s_mulk_i32 s11, 0x58
	v_add3_u32 v77, v92, v77, s22
	s_waitcnt lgkmcnt(2)
	v_bfe_u32 v80, v94, 16, 1
	s_sub_i32 s6, s6, s11
	v_lshrrev_b32_e32 v77, 16, v77
	v_add3_u32 v80, v94, v80, s22
	s_lshl_b32 s11, s6, 5
	s_lshl_b32 s6, s6, 6
	v_and_or_b32 v80, v80, s23, v77
	s_waitcnt lgkmcnt(1)
	v_bfe_u32 v77, v96, 16, 1
	s_and_b32 s6, s6, 0x1f00
	s_and_b32 s11, s11, 0x60
	v_add3_u32 v77, v96, v77, s22
	s_waitcnt lgkmcnt(0)
	v_bfe_u32 v81, v98, 16, 1
	s_or_b32 s11, s6, s11
	s_lshr_b32 s6, s10, 15
	v_lshrrev_b32_e32 v77, 16, v77
	v_add3_u32 v81, v98, v81, s22
	s_and_b32 s6, s6, 0x1ff80
	v_and_or_b32 v81, v81, s23, v77
	v_or_b32_e32 v77, s11, v199
	v_lshl_add_u64 v[84:85], v[68:69], 0, s[6:7]
	v_lshlrev_b32_e32 v100, 11, v77
	v_mov_b32_e32 v101, v67
	v_lshl_add_u64 v[100:101], v[84:85], 0, v[100:101]
	v_bfe_u32 v77, v83, 16, 1
	global_store_dwordx4 v[100:101], v[78:81], off sc1 nt
	v_add3_u32 v77, v83, v77, s22
	v_lshrrev_b32_e32 v77, 16, v77
	v_bfe_u32 v78, v87, 16, 1
	v_add3_u32 v78, v87, v78, s22
	v_and_or_b32 v78, v78, s23, v77
	v_bfe_u32 v77, v89, 16, 1
	v_add3_u32 v77, v89, v77, s22
	v_bfe_u32 v79, v91, 16, 1
	v_lshrrev_b32_e32 v77, 16, v77
	v_add3_u32 v79, v91, v79, s22
	v_and_or_b32 v79, v79, s23, v77
	v_bfe_u32 v77, v93, 16, 1
	v_add3_u32 v77, v93, v77, s22
	v_bfe_u32 v80, v95, 16, 1
	v_lshrrev_b32_e32 v77, 16, v77
	v_add3_u32 v80, v95, v80, s22
	v_and_or_b32 v80, v80, s23, v77
	v_bfe_u32 v77, v97, 16, 1
	v_add3_u32 v77, v97, v77, s22
	v_bfe_u32 v81, v99, 16, 1
	v_lshrrev_b32_e32 v77, 16, v77
	v_add3_u32 v81, v99, v81, s22
	v_and_or_b32 v81, v81, s23, v77
	v_or_b32_e32 v77, s11, v227
	v_lshlrev_b32_e32 v82, 11, v77
	v_mov_b32_e32 v83, v67
	ds_read2_b32 v[86:87], v75 offset0:16 offset1:24
	v_lshl_add_u64 v[82:83], v[84:85], 0, v[82:83]
	global_store_dwordx4 v[82:83], v[78:81], off sc1 nt
	ds_read2_b32 v[82:83], v75 offset0:49 offset1:57
	ds_read2_b32 v[88:89], v75 offset0:82 offset1:90
	ds_read2_b32 v[90:91], v75 offset0:115 offset1:123
	s_waitcnt lgkmcnt(3)
	v_bfe_u32 v77, v86, 16, 1
	v_add3_u32 v77, v86, v77, s22
	s_waitcnt lgkmcnt(2)
	v_bfe_u32 v78, v82, 16, 1
	ds_read2_b32 v[92:93], v75 offset0:148 offset1:156
	v_lshrrev_b32_e32 v77, 16, v77
	v_add3_u32 v78, v82, v78, s22
	ds_read2_b32 v[94:95], v75 offset0:181 offset1:189
	v_and_or_b32 v78, v78, s23, v77
	s_waitcnt lgkmcnt(3)
	v_bfe_u32 v77, v88, 16, 1
	v_add3_u32 v77, v88, v77, s22
	s_waitcnt lgkmcnt(2)
	v_bfe_u32 v79, v90, 16, 1
	ds_read2_b32 v[96:97], v75 offset0:214 offset1:222
	v_lshrrev_b32_e32 v77, 16, v77
	v_add3_u32 v79, v90, v79, s22
	ds_read2_b32 v[98:99], v75 offset0:247 offset1:255
	v_and_or_b32 v79, v79, s23, v77
	s_waitcnt lgkmcnt(3)
	v_bfe_u32 v77, v92, 16, 1
	v_add3_u32 v77, v92, v77, s22
	s_waitcnt lgkmcnt(2)
	v_bfe_u32 v80, v94, 16, 1
	v_lshrrev_b32_e32 v77, 16, v77
	v_add3_u32 v80, v94, v80, s22
	v_and_or_b32 v80, v80, s23, v77
	s_waitcnt lgkmcnt(1)
	v_bfe_u32 v77, v96, 16, 1
	v_add3_u32 v77, v96, v77, s22
	s_waitcnt lgkmcnt(0)
	v_bfe_u32 v81, v98, 16, 1
	v_lshrrev_b32_e32 v77, 16, v77
	v_add3_u32 v81, v98, v81, s22
	v_and_or_b32 v81, v81, s23, v77
	v_or_b32_e32 v77, s11, v228
	v_lshlrev_b32_e32 v100, 11, v77
	v_mov_b32_e32 v101, v67
	v_lshl_add_u64 v[100:101], v[84:85], 0, v[100:101]
	v_bfe_u32 v77, v87, 16, 1
	global_store_dwordx4 v[100:101], v[78:81], off sc1 nt
	v_add3_u32 v77, v87, v77, s22
	v_lshrrev_b32_e32 v77, 16, v77
	v_bfe_u32 v78, v83, 16, 1
	v_add3_u32 v78, v83, v78, s22
	v_and_or_b32 v78, v78, s23, v77
	v_bfe_u32 v77, v89, 16, 1
	v_add3_u32 v77, v89, v77, s22
	v_bfe_u32 v79, v91, 16, 1
	v_lshrrev_b32_e32 v77, 16, v77
	v_add3_u32 v79, v91, v79, s22
	v_and_or_b32 v79, v79, s23, v77
	v_bfe_u32 v77, v93, 16, 1
	v_add3_u32 v77, v93, v77, s22
	v_bfe_u32 v80, v95, 16, 1
	v_lshrrev_b32_e32 v77, 16, v77
	v_add3_u32 v80, v95, v80, s22
	v_and_or_b32 v80, v80, s23, v77
	v_bfe_u32 v77, v97, 16, 1
	v_add3_u32 v77, v97, v77, s22
	v_bfe_u32 v81, v99, 16, 1
	v_lshrrev_b32_e32 v77, 16, v77
	v_add3_u32 v81, v99, v81, s22
	v_and_or_b32 v81, v81, s23, v77
	v_or_b32_e32 v77, s11, v229
	v_lshlrev_b32_e32 v82, 11, v77
	v_mov_b32_e32 v83, v67
	v_lshl_add_u64 v[82:83], v[84:85], 0, v[82:83]
	global_store_dwordx4 v[82:83], v[78:81], off sc1 nt
	s_waitcnt lgkmcnt(0)

.LBB0_1025:
	s_andn2_b64 vcc, exec, s[10:11]
	s_cbranch_vccnz .LBB0_1027
	v_add_u32_e32 v77, v203, v226
	v_add_u32_e32 v78, 0x420, v77
	s_waitcnt vmcnt(15)
	ds_write2_b32 v77, v54, v55 offset1:1
	ds_write2_b32 v77, v56, v57 offset0:2 offset1:3
	s_waitcnt vmcnt(14)
	ds_write2_b32 v78, v50, v51 offset1:1
	v_add_u32_e32 v78, 0x428, v77
	ds_write2_b32 v78, v52, v53 offset1:1
	v_add_u32_e32 v78, 0x840, v77
	s_waitcnt vmcnt(13)
	ds_write2_b32 v78, v42, v43 offset1:1
	v_add_u32_e32 v78, 0x848, v77
	ds_write2_b32 v78, v44, v45 offset1:1
	v_add_u32_e32 v78, 0xc60, v77
	s_waitcnt vmcnt(12)
	ds_write2_b32 v78, v30, v31 offset1:1
	v_add_u32_e32 v78, 0xc68, v77
	ds_write2_b32 v78, v32, v33 offset1:1
	v_add_u32_e32 v78, 0x1080, v77
	s_waitcnt vmcnt(11)
	ds_write2_b32 v78, v34, v35 offset1:1
	v_add_u32_e32 v78, 0x1088, v77
	ds_write2_b32 v78, v36, v37 offset1:1
	v_add_u32_e32 v78, 0x14a0, v77
	s_waitcnt vmcnt(10)
	ds_write2_b32 v78, v22, v23 offset1:1
	v_add_u32_e32 v78, 0x14a8, v77
	ds_write2_b32 v78, v24, v25 offset1:1
	v_add_u32_e32 v78, 0x18c0, v77
	s_waitcnt vmcnt(9)
	ds_write2_b32 v78, v26, v27 offset1:1
	v_add_u32_e32 v78, 0x18c8, v77
	ds_write2_b32 v78, v28, v29 offset1:1
	v_add_u32_e32 v78, 0x1ce0, v77
	v_add_u32_e32 v77, 0x1ce8, v77
	s_waitcnt vmcnt(8)
	ds_write2_b32 v78, v10, v11 offset1:1
	ds_write2_b32 v77, v12, v13 offset1:1
	s_waitcnt lgkmcnt(0)
	ds_read2_b32 v[82:83], v75 offset1:8
	ds_read2_b32 v[86:87], v75 offset0:33 offset1:41
	ds_read2_b32 v[88:89], v75 offset0:66 offset1:74
	ds_read2_b32 v[90:91], v75 offset0:99 offset1:107
	ds_read2_b32 v[92:93], v75 offset0:132 offset1:140
	s_waitcnt lgkmcnt(4)
	v_bfe_u32 v77, v82, 16, 1
	v_add3_u32 v77, v82, v77, s22
	s_waitcnt lgkmcnt(3)
	v_bfe_u32 v78, v86, 16, 1
	v_lshrrev_b32_e32 v77, 16, v77
	v_add3_u32 v78, v86, v78, s22
	ds_read2_b32 v[94:95], v75 offset0:165 offset1:173
	v_and_or_b32 v78, v78, s23, v77
	s_waitcnt lgkmcnt(3)
	v_bfe_u32 v77, v88, 16, 1
	v_add3_u32 v77, v88, v77, s22
	s_waitcnt lgkmcnt(2)
	v_bfe_u32 v79, v90, 16, 1
	ds_read2_b32 v[96:97], v75 offset0:198 offset1:206
	v_lshrrev_b32_e32 v77, 16, v77
	v_add3_u32 v79, v90, v79, s22
	ds_read2_b32 v[98:99], v75 offset0:231 offset1:239
	v_and_or_b32 v79, v79, s23, v77
	s_waitcnt lgkmcnt(3)
	v_bfe_u32 v77, v92, 16, 1
	v_add3_u32 v77, v92, v77, s22
	s_waitcnt lgkmcnt(2)
	v_bfe_u32 v80, v94, 16, 1
	v_lshrrev_b32_e32 v77, 16, v77
	v_add3_u32 v80, v94, v80, s22
	v_and_or_b32 v80, v80, s23, v77
	s_waitcnt lgkmcnt(1)
	v_bfe_u32 v77, v96, 16, 1
	s_add_i32 s6, s20, 0xffff4000
	v_add3_u32 v77, v96, v77, s22
	s_waitcnt lgkmcnt(0)
	v_bfe_u32 v81, v98, 16, 1
	s_and_b32 s10, s21, 0xfc0
	s_and_b32 s11, s6, 0x3e0
	v_lshrrev_b32_e32 v77, 16, v77
	v_add3_u32 v81, v98, v81, s22
	s_lshl_b32 s6, s10, 1
	v_and_or_b32 v81, v81, s23, v77
	v_or_b32_e32 v77, s11, v199
	v_lshl_add_u64 v[84:85], v[70:71], 0, s[6:7]
	v_lshlrev_b32_e32 v100, 11, v77
	v_mov_b32_e32 v101, v67
	v_lshl_add_u64 v[100:101], v[84:85], 0, v[100:101]
	v_bfe_u32 v77, v83, 16, 1
	global_store_dwordx4 v[100:101], v[78:81], off sc1 nt
	v_add3_u32 v77, v83, v77, s22
	v_lshrrev_b32_e32 v77, 16, v77
	v_bfe_u32 v78, v87, 16, 1
	v_add3_u32 v78, v87, v78, s22
	v_and_or_b32 v78, v78, s23, v77
	v_bfe_u32 v77, v89, 16, 1
	v_add3_u32 v77, v89, v77, s22
	v_bfe_u32 v79, v91, 16, 1
	v_lshrrev_b32_e32 v77, 16, v77
	v_add3_u32 v79, v91, v79, s22
	v_and_or_b32 v79, v79, s23, v77
	v_bfe_u32 v77, v93, 16, 1
	v_add3_u32 v77, v93, v77, s22
	v_bfe_u32 v80, v95, 16, 1
	v_lshrrev_b32_e32 v77, 16, v77
	v_add3_u32 v80, v95, v80, s22
	v_and_or_b32 v80, v80, s23, v77
	v_bfe_u32 v77, v97, 16, 1
	v_add3_u32 v77, v97, v77, s22
	v_bfe_u32 v81, v99, 16, 1
	v_lshrrev_b32_e32 v77, 16, v77
	v_add3_u32 v81, v99, v81, s22
	v_and_or_b32 v81, v81, s23, v77
	v_or_b32_e32 v77, s11, v227
	v_lshlrev_b32_e32 v82, 11, v77
	v_mov_b32_e32 v83, v67
	ds_read2_b32 v[86:87], v75 offset0:16 offset1:24
	v_lshl_add_u64 v[82:83], v[84:85], 0, v[82:83]
	global_store_dwordx4 v[82:83], v[78:81], off sc1 nt
	ds_read2_b32 v[82:83], v75 offset0:49 offset1:57
	ds_read2_b32 v[88:89], v75 offset0:82 offset1:90
	ds_read2_b32 v[90:91], v75 offset0:115 offset1:123
	s_waitcnt lgkmcnt(3)
	v_bfe_u32 v77, v86, 16, 1
	v_add3_u32 v77, v86, v77, s22
	s_waitcnt lgkmcnt(2)
	v_bfe_u32 v78, v82, 16, 1
	ds_read2_b32 v[92:93], v75 offset0:148 offset1:156
	v_lshrrev_b32_e32 v77, 16, v77
	v_add3_u32 v78, v82, v78, s22
	ds_read2_b32 v[94:95], v75 offset0:181 offset1:189
	v_and_or_b32 v78, v78, s23, v77
	s_waitcnt lgkmcnt(3)
	v_bfe_u32 v77, v88, 16, 1
	v_add3_u32 v77, v88, v77, s22
	s_waitcnt lgkmcnt(2)
	v_bfe_u32 v79, v90, 16, 1
	ds_read2_b32 v[96:97], v75 offset0:214 offset1:222
	v_lshrrev_b32_e32 v77, 16, v77
	v_add3_u32 v79, v90, v79, s22
	ds_read2_b32 v[98:99], v75 offset0:247 offset1:255
	v_and_or_b32 v79, v79, s23, v77
	s_waitcnt lgkmcnt(3)
	v_bfe_u32 v77, v92, 16, 1
	v_add3_u32 v77, v92, v77, s22
	s_waitcnt lgkmcnt(2)
	v_bfe_u32 v80, v94, 16, 1
	v_lshrrev_b32_e32 v77, 16, v77
	v_add3_u32 v80, v94, v80, s22
	v_and_or_b32 v80, v80, s23, v77
	s_waitcnt lgkmcnt(1)
	v_bfe_u32 v77, v96, 16, 1
	v_add3_u32 v77, v96, v77, s22
	s_waitcnt lgkmcnt(0)
	v_bfe_u32 v81, v98, 16, 1
	v_lshrrev_b32_e32 v77, 16, v77
	v_add3_u32 v81, v98, v81, s22
	v_and_or_b32 v81, v81, s23, v77
	v_or_b32_e32 v77, s11, v228
	v_lshlrev_b32_e32 v100, 11, v77
	v_mov_b32_e32 v101, v67
	v_lshl_add_u64 v[100:101], v[84:85], 0, v[100:101]
	v_bfe_u32 v77, v87, 16, 1
	global_store_dwordx4 v[100:101], v[78:81], off sc1 nt
	v_add3_u32 v77, v87, v77, s22
	v_lshrrev_b32_e32 v77, 16, v77
	v_bfe_u32 v78, v83, 16, 1
	v_add3_u32 v78, v83, v78, s22
	v_and_or_b32 v78, v78, s23, v77
	v_bfe_u32 v77, v89, 16, 1
	v_add3_u32 v77, v89, v77, s22
	v_bfe_u32 v79, v91, 16, 1
	v_lshrrev_b32_e32 v77, 16, v77
	v_add3_u32 v79, v91, v79, s22
	v_and_or_b32 v79, v79, s23, v77
	v_bfe_u32 v77, v93, 16, 1
	v_add3_u32 v77, v93, v77, s22
	v_bfe_u32 v80, v95, 16, 1
	v_lshrrev_b32_e32 v77, 16, v77
	v_add3_u32 v80, v95, v80, s22
	v_and_or_b32 v80, v80, s23, v77
	v_bfe_u32 v77, v97, 16, 1
	v_add3_u32 v77, v97, v77, s22
	v_bfe_u32 v81, v99, 16, 1
	v_lshrrev_b32_e32 v77, 16, v77
	v_add3_u32 v81, v99, v81, s22
	v_and_or_b32 v81, v81, s23, v77
	v_or_b32_e32 v77, s11, v229
	v_lshlrev_b32_e32 v82, 11, v77
	v_mov_b32_e32 v83, v67
	v_lshl_add_u64 v[82:83], v[84:85], 0, v[82:83]
	global_store_dwordx4 v[82:83], v[78:81], off sc1 nt
	s_waitcnt lgkmcnt(0)

.LBB0_1033:
	s_mul_hi_i32 s6, s25, 0x2aaaaaab
	s_lshr_b32 s10, s6, 31
	s_ashr_i32 s6, s6, 4
	s_add_i32 s6, s6, s10
	s_mul_i32 s10, s6, 0xffffffa0
	s_add_i32 s11, s25, s10
	s_lshl_b32 s10, s6, 6
	s_cmp_lt_i32 s11, 16
	s_cselect_b64 vcc, -1, 0
	v_cndmask_b32_e32 v78, 1.0, v76, vcc
	s_waitcnt vmcnt(15)
	v_pk_mul_f32 v[54:55], v[78:79], v[54:55] op_sel_hi:[0,1]
	v_add_u32_e32 v77, v203, v226
	ds_write2_b32 v77, v54, v55 offset1:1
	v_pk_mul_f32 v[54:55], v[78:79], v[56:57] op_sel_hi:[0,1]
	ds_write2_b32 v77, v54, v55 offset0:2 offset1:3
	s_waitcnt vmcnt(14)
	v_pk_mul_f32 v[50:51], v[78:79], v[50:51] op_sel_hi:[0,1]
	v_add_u32_e32 v54, 0x420, v77
	ds_write2_b32 v54, v50, v51 offset1:1
	v_pk_mul_f32 v[50:51], v[78:79], v[52:53] op_sel_hi:[0,1]
	v_add_u32_e32 v52, 0x428, v77
	ds_write2_b32 v52, v50, v51 offset1:1
	s_waitcnt vmcnt(13)
	v_pk_mul_f32 v[42:43], v[78:79], v[42:43] op_sel_hi:[0,1]
	v_add_u32_e32 v50, 0x840, v77
	ds_write2_b32 v50, v42, v43 offset1:1
	v_pk_mul_f32 v[42:43], v[78:79], v[44:45] op_sel_hi:[0,1]
	v_add_u32_e32 v44, 0x848, v77
	ds_write2_b32 v44, v42, v43 offset1:1
	s_waitcnt vmcnt(12)
	v_pk_mul_f32 v[30:31], v[78:79], v[30:31] op_sel_hi:[0,1]
	v_add_u32_e32 v42, 0xc60, v77
	ds_write2_b32 v42, v30, v31 offset1:1
	v_pk_mul_f32 v[30:31], v[78:79], v[32:33] op_sel_hi:[0,1]
	v_add_u32_e32 v32, 0xc68, v77
	ds_write2_b32 v32, v30, v31 offset1:1
	s_waitcnt vmcnt(11)
	v_pk_mul_f32 v[30:31], v[78:79], v[34:35] op_sel_hi:[0,1]
	v_add_u32_e32 v32, 0x1080, v77
	ds_write2_b32 v32, v30, v31 offset1:1
	v_pk_mul_f32 v[30:31], v[78:79], v[36:37] op_sel_hi:[0,1]
	v_add_u32_e32 v32, 0x1088, v77
	ds_write2_b32 v32, v30, v31 offset1:1
	s_waitcnt vmcnt(10)
	v_pk_mul_f32 v[22:23], v[78:79], v[22:23] op_sel_hi:[0,1]
	v_add_u32_e32 v30, 0x14a0, v77
	ds_write2_b32 v30, v22, v23 offset1:1
	v_pk_mul_f32 v[22:23], v[78:79], v[24:25] op_sel_hi:[0,1]
	v_add_u32_e32 v24, 0x14a8, v77
	ds_write2_b32 v24, v22, v23 offset1:1
	s_waitcnt vmcnt(9)
	v_pk_mul_f32 v[22:23], v[26:27], v[78:79] op_sel_hi:[1,0]
	v_add_u32_e32 v24, 0x18c0, v77
	ds_write2_b32 v24, v22, v23 offset1:1
	v_pk_mul_f32 v[22:23], v[28:29], v[78:79] op_sel_hi:[1,0]
	v_add_u32_e32 v24, 0x18c8, v77
	ds_write2_b32 v24, v22, v23 offset1:1
	s_waitcnt vmcnt(8)
	v_pk_mul_f32 v[10:11], v[10:11], v[78:79] op_sel_hi:[1,0]
	v_add_u32_e32 v22, 0x1ce0, v77
	ds_write2_b32 v22, v10, v11 offset1:1
	v_pk_mul_f32 v[10:11], v[12:13], v[78:79] op_sel_hi:[1,0]
	v_add_u32_e32 v12, 0x1ce8, v77
	ds_write2_b32 v12, v10, v11 offset1:1
	s_waitcnt lgkmcnt(0)
	ds_read2_b32 v[22:23], v75 offset1:8
	ds_read2_b32 v[26:27], v75 offset0:33 offset1:41
	ds_read2_b32 v[28:29], v75 offset0:66 offset1:74
	ds_read2_b32 v[30:31], v75 offset0:99 offset1:107
	ds_read2_b32 v[32:33], v75 offset0:132 offset1:140
	s_waitcnt lgkmcnt(4)
	v_bfe_u32 v10, v22, 16, 1
	v_add3_u32 v10, v22, v10, s22
	s_waitcnt lgkmcnt(3)
	v_bfe_u32 v11, v26, 16, 1
	v_lshrrev_b32_e32 v10, 16, v10
	v_add3_u32 v11, v26, v11, s22
	ds_read2_b32 v[34:35], v75 offset0:165 offset1:173
	v_and_or_b32 v10, v11, s23, v10
	s_waitcnt lgkmcnt(3)
	v_bfe_u32 v11, v28, 16, 1
	v_add3_u32 v11, v28, v11, s22
	s_waitcnt lgkmcnt(2)
	v_bfe_u32 v12, v30, 16, 1
	ds_read2_b32 v[36:37], v75 offset0:198 offset1:206
	v_lshrrev_b32_e32 v11, 16, v11
	v_add3_u32 v12, v30, v12, s22
	ds_read2_b32 v[42:43], v75 offset0:231 offset1:239
	v_and_or_b32 v11, v12, s23, v11
	s_waitcnt lgkmcnt(3)
	v_bfe_u32 v12, v32, 16, 1
	v_add3_u32 v12, v32, v12, s22
	s_waitcnt lgkmcnt(2)
	v_bfe_u32 v13, v34, 16, 1
	s_mulk_i32 s6, 0xf400
	v_lshrrev_b32_e32 v12, 16, v12
	v_add3_u32 v13, v34, v13, s22
	s_add_i32 s6, s6, s20
	v_and_or_b32 v12, v13, s23, v12
	s_waitcnt lgkmcnt(1)
	v_bfe_u32 v13, v36, 16, 1
	v_add_u32_e32 v44, s6, v199
	s_ashr_i32 s11, s10, 31
	v_add3_u32 v13, v36, v13, s22
	s_waitcnt lgkmcnt(0)
	v_bfe_u32 v22, v42, 16, 1
	v_ashrrev_i32_e32 v45, 31, v44
	v_lshl_add_u64 v[24:25], s[10:11], 1, v[72:73]
	v_lshrrev_b32_e32 v13, 16, v13
	v_add3_u32 v22, v42, v22, s22
	v_lshlrev_b64 v[50:51], 11, v[44:45]
	v_and_or_b32 v13, v22, s23, v13
	v_lshl_add_u64 v[50:51], v[24:25], 0, v[50:51]
	global_store_dwordx4 v[50:51], v[10:13], off sc1 nt
	v_bfe_u32 v22, v43, 16, 1
	v_add3_u32 v22, v43, v22, s22
	v_bfe_u32 v10, v23, 16, 1
	v_add3_u32 v10, v23, v10, s22
	v_bfe_u32 v11, v27, 16, 1
	v_lshrrev_b32_e32 v10, 16, v10
	v_add3_u32 v11, v27, v11, s22
	v_and_or_b32 v10, v11, s23, v10
	v_bfe_u32 v11, v29, 16, 1
	v_add3_u32 v11, v29, v11, s22
	v_bfe_u32 v12, v31, 16, 1
	v_lshrrev_b32_e32 v11, 16, v11
	v_add3_u32 v12, v31, v12, s22
	v_and_or_b32 v11, v12, s23, v11
	v_bfe_u32 v12, v33, 16, 1
	v_add3_u32 v12, v33, v12, s22
	v_bfe_u32 v13, v35, 16, 1
	v_lshrrev_b32_e32 v12, 16, v12
	v_add3_u32 v13, v35, v13, s22
	v_and_or_b32 v12, v13, s23, v12
	v_bfe_u32 v13, v37, 16, 1
	v_add3_u32 v13, v37, v13, s22
	v_lshrrev_b32_e32 v13, 16, v13
	v_and_or_b32 v13, v22, s23, v13
	v_add_u32_e32 v22, 8, v44
	v_ashrrev_i32_e32 v23, 31, v22
	v_lshlrev_b64 v[22:23], 11, v[22:23]
	ds_read2_b32 v[26:27], v75 offset0:16 offset1:24
	v_lshl_add_u64 v[22:23], v[24:25], 0, v[22:23]
	global_store_dwordx4 v[22:23], v[10:13], off sc1 nt
	ds_read2_b32 v[22:23], v75 offset0:49 offset1:57
	ds_read2_b32 v[28:29], v75 offset0:82 offset1:90
	ds_read2_b32 v[30:31], v75 offset0:115 offset1:123
	s_waitcnt lgkmcnt(3)
	v_bfe_u32 v10, v26, 16, 1
	v_add3_u32 v10, v26, v10, s22
	s_waitcnt lgkmcnt(2)
	v_bfe_u32 v11, v22, 16, 1
	ds_read2_b32 v[32:33], v75 offset0:148 offset1:156
	v_lshrrev_b32_e32 v10, 16, v10
	v_add3_u32 v11, v22, v11, s22
	ds_read2_b32 v[34:35], v75 offset0:181 offset1:189
	v_and_or_b32 v10, v11, s23, v10
	s_waitcnt lgkmcnt(3)
	v_bfe_u32 v11, v28, 16, 1
	v_add3_u32 v11, v28, v11, s22
	s_waitcnt lgkmcnt(2)
	v_bfe_u32 v12, v30, 16, 1
	ds_read2_b32 v[36:37], v75 offset0:214 offset1:222
	v_lshrrev_b32_e32 v11, 16, v11
	v_add3_u32 v12, v30, v12, s22
	ds_read2_b32 v[42:43], v75 offset0:247 offset1:255
	v_and_or_b32 v11, v12, s23, v11
	s_waitcnt lgkmcnt(3)
	v_bfe_u32 v12, v32, 16, 1
	v_add3_u32 v12, v32, v12, s22
	s_waitcnt lgkmcnt(2)
	v_bfe_u32 v13, v34, 16, 1
	v_lshrrev_b32_e32 v12, 16, v12
	v_add3_u32 v13, v34, v13, s22
	v_and_or_b32 v12, v13, s23, v12
	s_waitcnt lgkmcnt(1)
	v_bfe_u32 v13, v36, 16, 1
	v_add_u32_e32 v50, 16, v44
	v_add3_u32 v13, v36, v13, s22
	s_waitcnt lgkmcnt(0)
	v_bfe_u32 v22, v42, 16, 1
	v_ashrrev_i32_e32 v51, 31, v50
	v_lshrrev_b32_e32 v13, 16, v13
	v_add3_u32 v22, v42, v22, s22
	v_lshlrev_b64 v[50:51], 11, v[50:51]
	v_and_or_b32 v13, v22, s23, v13
	v_lshl_add_u64 v[50:51], v[24:25], 0, v[50:51]
	global_store_dwordx4 v[50:51], v[10:13], off sc1 nt
	v_bfe_u32 v22, v43, 16, 1
	v_add3_u32 v22, v43, v22, s22
	v_bfe_u32 v10, v27, 16, 1
	v_add3_u32 v10, v27, v10, s22
	v_bfe_u32 v11, v23, 16, 1
	v_lshrrev_b32_e32 v10, 16, v10
	v_add3_u32 v11, v23, v11, s22
	v_and_or_b32 v10, v11, s23, v10
	v_bfe_u32 v11, v29, 16, 1
	v_add3_u32 v11, v29, v11, s22
	v_bfe_u32 v12, v31, 16, 1
	v_lshrrev_b32_e32 v11, 16, v11
	v_add3_u32 v12, v31, v12, s22
	v_and_or_b32 v11, v12, s23, v11
	v_bfe_u32 v12, v33, 16, 1
	v_add3_u32 v12, v33, v12, s22
	v_bfe_u32 v13, v35, 16, 1
	v_lshrrev_b32_e32 v12, 16, v12
	v_add3_u32 v13, v35, v13, s22
	v_and_or_b32 v12, v13, s23, v12
	v_bfe_u32 v13, v37, 16, 1
	v_add3_u32 v13, v37, v13, s22
	v_lshrrev_b32_e32 v13, 16, v13
	v_and_or_b32 v13, v22, s23, v13
	v_add_u32_e32 v22, 24, v44
	v_ashrrev_i32_e32 v23, 31, v22
	v_lshlrev_b64 v[22:23], 11, v[22:23]
	v_lshl_add_u64 v[22:23], v[24:25], 0, v[22:23]
	global_store_dwordx4 v[22:23], v[10:13], off sc1 nt
	s_waitcnt lgkmcnt(0)
	s_branch .LBB0_1012
